# hand-written pipelined final rmsnorm phase only (gains hoisted, double-buffered row loads)
# speedup vs baseline: 1.0114x; 1.0114x over previous
.LBB0_569:
	s_or_b64 exec, exec, s[0:1]
	s_barrier
	v_and_b32_e32 v0, 63, v212
	v_readfirstlane_b32 s0, v212
	v_lshlrev_b32_e32 v1, 4, v0
	v_lshlrev_b32_e32 v2, 5, v0
	s_lshr_b32 s0, s0, 6
	s_lshl_b32 s0, s0, 3
	s_add_i32 s0, s0, s66
	s_mov_b32 s1, 0
	v_add_u32_e32 v3, 0x1000, v2
	s_lshl_b64 s[2:3], s[0:1], 12
	s_add_u32 s2, s2, s20
	s_addc_u32 s3, s3, s21
	s_lshl_b64 s[4:5], s[0:1], 13
	s_add_u32 s4, s4, s30
	s_addc_u32 s5, s5, s31
	global_load_dwordx4 v[100:103], v2, s[28:29]
	global_load_dwordx4 v[104:107], v2, s[28:29] offset:16
	global_load_dwordx4 v[108:111], v2, s[28:29] offset:2048
	global_load_dwordx4 v[112:115], v2, s[28:29] offset:2064
	global_load_dwordx4 v[116:119], v3, s[28:29]
	global_load_dwordx4 v[120:123], v3, s[28:29] offset:16
	global_load_dwordx4 v[124:127], v3, s[28:29] offset:2048
	global_load_dwordx4 v[128:131], v3, s[28:29] offset:2064
	global_load_dwordx4 v[16:19], v1, s[2:3] nt
	global_load_dwordx4 v[20:23], v1, s[2:3] offset:1024 nt
	global_load_dwordx4 v[24:27], v1, s[2:3] offset:2048 nt
	global_load_dwordx4 v[28:31], v1, s[2:3] offset:3072 nt
	v_xor_b32_e32 v6, 1, v0
	v_xor_b32_e32 v7, 2, v0
	v_xor_b32_e32 v8, 4, v0
	v_xor_b32_e32 v9, 8, v0
	v_xor_b32_e32 v10, 16, v0
	v_xor_b32_e32 v11, 32, v0
	v_lshlrev_b32_e32 v6, 2, v6
	v_lshlrev_b32_e32 v7, 2, v7
	v_lshlrev_b32_e32 v8, 2, v8
	v_lshlrev_b32_e32 v9, 2, v9
	v_lshlrev_b32_e32 v10, 2, v10
	v_lshlrev_b32_e32 v11, 2, v11
	v_mov_b32_e32 v84, 0x358637bd
	s_mov_b32 s6, 0
	s_waitcnt vmcnt(0)
.Lp11_loop:
	s_add_u32 s8, s2, 0x1000
	s_addc_u32 s9, s3, 0
	global_load_dwordx4 v[32:35], v1, s[8:9] nt
	global_load_dwordx4 v[36:39], v1, s[8:9] offset:1024 nt
	global_load_dwordx4 v[40:43], v1, s[8:9] offset:2048 nt
	global_load_dwordx4 v[44:47], v1, s[8:9] offset:3072 nt
	s_waitcnt vmcnt(12)
	v_lshlrev_b32_e32 v48, 16, v16
	v_and_b32_e32 v49, 0xffff0000, v16
	v_lshlrev_b32_e32 v50, 16, v17
	v_and_b32_e32 v51, 0xffff0000, v17
	v_lshlrev_b32_e32 v52, 16, v18
	v_and_b32_e32 v53, 0xffff0000, v18
	v_lshlrev_b32_e32 v54, 16, v19
	v_and_b32_e32 v55, 0xffff0000, v19
	v_lshlrev_b32_e32 v56, 16, v20
	v_and_b32_e32 v57, 0xffff0000, v20
	v_lshlrev_b32_e32 v58, 16, v21
	v_and_b32_e32 v59, 0xffff0000, v21
	v_lshlrev_b32_e32 v60, 16, v22
	v_and_b32_e32 v61, 0xffff0000, v22
	v_lshlrev_b32_e32 v62, 16, v23
	v_and_b32_e32 v63, 0xffff0000, v23
	v_lshlrev_b32_e32 v64, 16, v24
	v_and_b32_e32 v65, 0xffff0000, v24
	v_lshlrev_b32_e32 v66, 16, v25
	v_and_b32_e32 v67, 0xffff0000, v25
	v_lshlrev_b32_e32 v68, 16, v26
	v_and_b32_e32 v69, 0xffff0000, v26
	v_lshlrev_b32_e32 v70, 16, v27
	v_and_b32_e32 v71, 0xffff0000, v27
	v_lshlrev_b32_e32 v72, 16, v28
	v_and_b32_e32 v73, 0xffff0000, v28
	v_lshlrev_b32_e32 v74, 16, v29
	v_and_b32_e32 v75, 0xffff0000, v29
	v_lshlrev_b32_e32 v76, 16, v30
	v_and_b32_e32 v77, 0xffff0000, v30
	v_lshlrev_b32_e32 v78, 16, v31
	v_and_b32_e32 v79, 0xffff0000, v31
	v_pk_mul_f32 v[80:81], v[48:49], v[48:49]
	v_pk_fma_f32 v[80:81], v[50:51], v[50:51], v[80:81]
	v_pk_fma_f32 v[80:81], v[52:53], v[52:53], v[80:81]
	v_pk_fma_f32 v[80:81], v[54:55], v[54:55], v[80:81]
	v_pk_fma_f32 v[80:81], v[56:57], v[56:57], v[80:81]
	v_pk_fma_f32 v[80:81], v[58:59], v[58:59], v[80:81]
	v_pk_fma_f32 v[80:81], v[60:61], v[60:61], v[80:81]
	v_pk_fma_f32 v[80:81], v[62:63], v[62:63], v[80:81]
	v_pk_fma_f32 v[80:81], v[64:65], v[64:65], v[80:81]
	v_pk_fma_f32 v[80:81], v[66:67], v[66:67], v[80:81]
	v_pk_fma_f32 v[80:81], v[68:69], v[68:69], v[80:81]
	v_pk_fma_f32 v[80:81], v[70:71], v[70:71], v[80:81]
	v_pk_fma_f32 v[80:81], v[72:73], v[72:73], v[80:81]
	v_pk_fma_f32 v[80:81], v[74:75], v[74:75], v[80:81]
	v_pk_fma_f32 v[80:81], v[76:77], v[76:77], v[80:81]
	v_pk_fma_f32 v[80:81], v[78:79], v[78:79], v[80:81]
	v_add_f32_e32 v82, v80, v81
	ds_bpermute_b32 v83, v6, v82
	s_waitcnt lgkmcnt(0)
	v_add_f32_e32 v82, v82, v83
	ds_bpermute_b32 v83, v7, v82
	s_waitcnt lgkmcnt(0)
	v_add_f32_e32 v82, v82, v83
	ds_bpermute_b32 v83, v8, v82
	s_waitcnt lgkmcnt(0)
	v_add_f32_e32 v82, v82, v83
	ds_bpermute_b32 v83, v9, v82
	s_waitcnt lgkmcnt(0)
	v_add_f32_e32 v82, v82, v83
	ds_bpermute_b32 v83, v10, v82
	s_waitcnt lgkmcnt(0)
	v_add_f32_e32 v82, v82, v83
	ds_bpermute_b32 v83, v11, v82
	s_waitcnt lgkmcnt(0)
	v_add_f32_e32 v82, v82, v83
	v_fmamk_f32 v82, v82, 0x3a000000, v84
	v_rsq_f32_e32 v82, v82
	s_nop 0
	v_mov_b32_e32 v83, v82
	v_pk_mul_f32 v[48:49], v[48:49], v[82:83]
	v_pk_mul_f32 v[50:51], v[50:51], v[82:83]
	v_pk_mul_f32 v[52:53], v[52:53], v[82:83]
	v_pk_mul_f32 v[54:55], v[54:55], v[82:83]
	v_pk_mul_f32 v[56:57], v[56:57], v[82:83]
	v_pk_mul_f32 v[58:59], v[58:59], v[82:83]
	v_pk_mul_f32 v[60:61], v[60:61], v[82:83]
	v_pk_mul_f32 v[62:63], v[62:63], v[82:83]
	v_pk_mul_f32 v[64:65], v[64:65], v[82:83]
	v_pk_mul_f32 v[66:67], v[66:67], v[82:83]
	v_pk_mul_f32 v[68:69], v[68:69], v[82:83]
	v_pk_mul_f32 v[70:71], v[70:71], v[82:83]
	v_pk_mul_f32 v[72:73], v[72:73], v[82:83]
	v_pk_mul_f32 v[74:75], v[74:75], v[82:83]
	v_pk_mul_f32 v[76:77], v[76:77], v[82:83]
	v_pk_mul_f32 v[78:79], v[78:79], v[82:83]
	v_pk_mul_f32 v[48:49], v[48:49], v[100:101]
	v_pk_mul_f32 v[50:51], v[50:51], v[102:103]
	v_pk_mul_f32 v[52:53], v[52:53], v[104:105]
	v_pk_mul_f32 v[54:55], v[54:55], v[106:107]
	v_pk_mul_f32 v[56:57], v[56:57], v[108:109]
	v_pk_mul_f32 v[58:59], v[58:59], v[110:111]
	v_pk_mul_f32 v[60:61], v[60:61], v[112:113]
	v_pk_mul_f32 v[62:63], v[62:63], v[114:115]
	v_pk_mul_f32 v[64:65], v[64:65], v[116:117]
	v_pk_mul_f32 v[66:67], v[66:67], v[118:119]
	v_pk_mul_f32 v[68:69], v[68:69], v[120:121]
	v_pk_mul_f32 v[70:71], v[70:71], v[122:123]
	v_pk_mul_f32 v[72:73], v[72:73], v[124:125]
	v_pk_mul_f32 v[74:75], v[74:75], v[126:127]
	v_pk_mul_f32 v[76:77], v[76:77], v[128:129]
	v_pk_mul_f32 v[78:79], v[78:79], v[130:131]
	global_store_dwordx4 v2, v[48:51], s[4:5] nt
	global_store_dwordx4 v2, v[52:55], s[4:5] offset:16 nt
	global_store_dwordx4 v2, v[56:59], s[4:5] offset:2048 nt
	global_store_dwordx4 v2, v[60:63], s[4:5] offset:2064 nt
	global_store_dwordx4 v3, v[64:67], s[4:5] nt
	global_store_dwordx4 v3, v[68:71], s[4:5] offset:16 nt
	global_store_dwordx4 v3, v[72:75], s[4:5] offset:2048 nt
	global_store_dwordx4 v3, v[76:79], s[4:5] offset:2064 nt
	s_add_u32 s2, s2, 0x2000
	s_addc_u32 s3, s3, 0
	global_load_dwordx4 v[16:19], v1, s[2:3] nt
	global_load_dwordx4 v[20:23], v1, s[2:3] offset:1024 nt
	global_load_dwordx4 v[24:27], v1, s[2:3] offset:2048 nt
	global_load_dwordx4 v[28:31], v1, s[2:3] offset:3072 nt
	s_waitcnt vmcnt(12)
	s_add_u32 s10, s4, 0x2000
	s_addc_u32 s11, s5, 0
	v_lshlrev_b32_e32 v48, 16, v32
	v_and_b32_e32 v49, 0xffff0000, v32
	v_lshlrev_b32_e32 v50, 16, v33
	v_and_b32_e32 v51, 0xffff0000, v33
	v_lshlrev_b32_e32 v52, 16, v34
	v_and_b32_e32 v53, 0xffff0000, v34
	v_lshlrev_b32_e32 v54, 16, v35
	v_and_b32_e32 v55, 0xffff0000, v35
	v_lshlrev_b32_e32 v56, 16, v36
	v_and_b32_e32 v57, 0xffff0000, v36
	v_lshlrev_b32_e32 v58, 16, v37
	v_and_b32_e32 v59, 0xffff0000, v37
	v_lshlrev_b32_e32 v60, 16, v38
	v_and_b32_e32 v61, 0xffff0000, v38
	v_lshlrev_b32_e32 v62, 16, v39
	v_and_b32_e32 v63, 0xffff0000, v39
	v_lshlrev_b32_e32 v64, 16, v40
	v_and_b32_e32 v65, 0xffff0000, v40
	v_lshlrev_b32_e32 v66, 16, v41
	v_and_b32_e32 v67, 0xffff0000, v41
	v_lshlrev_b32_e32 v68, 16, v42
	v_and_b32_e32 v69, 0xffff0000, v42
	v_lshlrev_b32_e32 v70, 16, v43
	v_and_b32_e32 v71, 0xffff0000, v43
	v_lshlrev_b32_e32 v72, 16, v44
	v_and_b32_e32 v73, 0xffff0000, v44
	v_lshlrev_b32_e32 v74, 16, v45
	v_and_b32_e32 v75, 0xffff0000, v45
	v_lshlrev_b32_e32 v76, 16, v46
	v_and_b32_e32 v77, 0xffff0000, v46
	v_lshlrev_b32_e32 v78, 16, v47
	v_and_b32_e32 v79, 0xffff0000, v47
	v_pk_mul_f32 v[80:81], v[48:49], v[48:49]
	v_pk_fma_f32 v[80:81], v[50:51], v[50:51], v[80:81]
	v_pk_fma_f32 v[80:81], v[52:53], v[52:53], v[80:81]
	v_pk_fma_f32 v[80:81], v[54:55], v[54:55], v[80:81]
	v_pk_fma_f32 v[80:81], v[56:57], v[56:57], v[80:81]
	v_pk_fma_f32 v[80:81], v[58:59], v[58:59], v[80:81]
	v_pk_fma_f32 v[80:81], v[60:61], v[60:61], v[80:81]
	v_pk_fma_f32 v[80:81], v[62:63], v[62:63], v[80:81]
	v_pk_fma_f32 v[80:81], v[64:65], v[64:65], v[80:81]
	v_pk_fma_f32 v[80:81], v[66:67], v[66:67], v[80:81]
	v_pk_fma_f32 v[80:81], v[68:69], v[68:69], v[80:81]
	v_pk_fma_f32 v[80:81], v[70:71], v[70:71], v[80:81]
	v_pk_fma_f32 v[80:81], v[72:73], v[72:73], v[80:81]
	v_pk_fma_f32 v[80:81], v[74:75], v[74:75], v[80:81]
	v_pk_fma_f32 v[80:81], v[76:77], v[76:77], v[80:81]
	v_pk_fma_f32 v[80:81], v[78:79], v[78:79], v[80:81]
	v_add_f32_e32 v82, v80, v81
	ds_bpermute_b32 v83, v6, v82
	s_waitcnt lgkmcnt(0)
	v_add_f32_e32 v82, v82, v83
	ds_bpermute_b32 v83, v7, v82
	s_waitcnt lgkmcnt(0)
	v_add_f32_e32 v82, v82, v83
	ds_bpermute_b32 v83, v8, v82
	s_waitcnt lgkmcnt(0)
	v_add_f32_e32 v82, v82, v83
	ds_bpermute_b32 v83, v9, v82
	s_waitcnt lgkmcnt(0)
	v_add_f32_e32 v82, v82, v83
	ds_bpermute_b32 v83, v10, v82
	s_waitcnt lgkmcnt(0)
	v_add_f32_e32 v82, v82, v83
	ds_bpermute_b32 v83, v11, v82
	s_waitcnt lgkmcnt(0)
	v_add_f32_e32 v82, v82, v83
	v_fmamk_f32 v82, v82, 0x3a000000, v84
	v_rsq_f32_e32 v82, v82
	s_nop 0
	v_mov_b32_e32 v83, v82
	v_pk_mul_f32 v[48:49], v[48:49], v[82:83]
	v_pk_mul_f32 v[50:51], v[50:51], v[82:83]
	v_pk_mul_f32 v[52:53], v[52:53], v[82:83]
	v_pk_mul_f32 v[54:55], v[54:55], v[82:83]
	v_pk_mul_f32 v[56:57], v[56:57], v[82:83]
	v_pk_mul_f32 v[58:59], v[58:59], v[82:83]
	v_pk_mul_f32 v[60:61], v[60:61], v[82:83]
	v_pk_mul_f32 v[62:63], v[62:63], v[82:83]
	v_pk_mul_f32 v[64:65], v[64:65], v[82:83]
	v_pk_mul_f32 v[66:67], v[66:67], v[82:83]
	v_pk_mul_f32 v[68:69], v[68:69], v[82:83]
	v_pk_mul_f32 v[70:71], v[70:71], v[82:83]
	v_pk_mul_f32 v[72:73], v[72:73], v[82:83]
	v_pk_mul_f32 v[74:75], v[74:75], v[82:83]
	v_pk_mul_f32 v[76:77], v[76:77], v[82:83]
	v_pk_mul_f32 v[78:79], v[78:79], v[82:83]
	v_pk_mul_f32 v[48:49], v[48:49], v[100:101]
	v_pk_mul_f32 v[50:51], v[50:51], v[102:103]
	v_pk_mul_f32 v[52:53], v[52:53], v[104:105]
	v_pk_mul_f32 v[54:55], v[54:55], v[106:107]
	v_pk_mul_f32 v[56:57], v[56:57], v[108:109]
	v_pk_mul_f32 v[58:59], v[58:59], v[110:111]
	v_pk_mul_f32 v[60:61], v[60:61], v[112:113]
	v_pk_mul_f32 v[62:63], v[62:63], v[114:115]
	v_pk_mul_f32 v[64:65], v[64:65], v[116:117]
	v_pk_mul_f32 v[66:67], v[66:67], v[118:119]
	v_pk_mul_f32 v[68:69], v[68:69], v[120:121]
	v_pk_mul_f32 v[70:71], v[70:71], v[122:123]
	v_pk_mul_f32 v[72:73], v[72:73], v[124:125]
	v_pk_mul_f32 v[74:75], v[74:75], v[126:127]
	v_pk_mul_f32 v[76:77], v[76:77], v[128:129]
	v_pk_mul_f32 v[78:79], v[78:79], v[130:131]
	global_store_dwordx4 v2, v[48:51], s[10:11] nt
	global_store_dwordx4 v2, v[52:55], s[10:11] offset:16 nt
	global_store_dwordx4 v2, v[56:59], s[10:11] offset:2048 nt
	global_store_dwordx4 v2, v[60:63], s[10:11] offset:2064 nt
	global_store_dwordx4 v3, v[64:67], s[10:11] nt
	global_store_dwordx4 v3, v[68:71], s[10:11] offset:16 nt
	global_store_dwordx4 v3, v[72:75], s[10:11] offset:2048 nt
	global_store_dwordx4 v3, v[76:79], s[10:11] offset:2064 nt
	s_add_u32 s4, s4, 0x4000
	s_addc_u32 s5, s5, 0
	s_add_i32 s6, s6, 2
	s_cmp_lt_u32 s6, 8
	s_cbranch_scc1 .Lp11_loop
	s_endpgm
